# attn-C pipelined loop plus one static s_setprio 1 for waves 4-7 inside the C tile loop
# baseline (speedup 1.0000x reference)
; __device__ __forceinline__ void attn_c_unit(LAS unsigned char* lds, const bf16_t* proj, const bf16_t* vt, bf16_t* obuf, int b, int hk, int blk, float mref, unsigned long long* sg) {
;     int tid_ = threadIdx.x; asm volatile("" : "+v"(tid_));
;     const int tid = tid_, lane = tid & 63, r = lane & 31, h = lane >> 5;
;     const int w = __builtin_amdgcn_readfirstlane(tid >> 6);
;     const int qhead = 4 * hk + (w >> 1), qpos = blk * 128 + 64 * (w & 1) + r, qcol = QC_OFF + 64 * qhead, kcol = KC_OFF + 64 * hk, vslot = 10 + hk, ocol = 1024 + 64 * qhead;
;     const size_t tokbase = (size_t)b * SEQ;
;     const int srow = tid >> 3, sch = tid & 7;
;     const bf16_t* kg = proj + (tokbase + srow) * INW + kcol + sch * 8;
;     const bf16_t* vg = vt + ((size_t)(b * NVS + vslot) * 64 + srow) * SEQ + sch * 8;
;     const unsigned sdst = srow * KP + sch * 16;
;     u32x4 kreg, vreg;
;     const bf16_t* qg = proj + (tokbase + qpos) * INW + qcol + 8 * h;
;     bf16x8 qf[2][4];
; #pragma unroll
;     for (int j = 0; j < 2; ++j)
; #pragma unroll
;         for (int ks = 0; ks < 4; ++ks) qf[j][ks] = *(const bf16x8*)(qg + (size_t)(32 * j) * INW + 16 * ks);
;     f32x16 negm;
; #pragma unroll
;     for (int i = 0; i < 16; ++i) negm[i] = 0.f;
;     float l0 = 0.f, l1 = 0.f;
;     f32x16 o00, o01, o10, o11;
; #pragma unroll
;     for (int i = 0; i < 16; ++i) { o00[i] = 0.f; o01[i] = 0.f; o10[i] = 0.f; o11[i] = 0.f; }
;     const int pr = (r & ~12) | ((r & 4) << 1) | ((r & 8) >> 1);
;     constexpr int nT = SEQ / 64;
;     constexpr int CK = 0, CV = 4 * ATT_TILE;
; #pragma unroll
;     for (int i = 0; i < 2; ++i) { kreg = *(const u32x4*)(kg + (size_t)(i * 64) * INW); vreg = *(const u32x4*)(vg + i * 64);
;         *(LAS u32x4*)(lds + CK + i * ATT_TILE + sdst) = kreg; *(LAS u32x4*)(lds + CV + i * ATT_TILE + sdst) = vreg; }
;     __syncthreads();
;     for (int it = 0; it < nT; ++it) {
;         const int buf = it & 3;
;         if (it + 2 < nT) { kreg = *(const u32x4*)(kg + (size_t)((it + 2) * 64) * INW); vreg = *(const u32x4*)(vg + (it + 2) * 64); }
;         const LAS unsigned char* kb = lds + CK + buf * ATT_TILE + pr * KP + 16 * h;
;         f32x16 s00, s01, s10, s11;
;         {
;             const bf16x8 a0 = *(const LAS bf16x8*)(kb), a1 = *(const LAS bf16x8*)(kb + 32 * KP);
;             s00 = __builtin_amdgcn_mfma_f32_32x32x16_bf16(a0, qf[0][0], negm, 0, 0, 0);
.LBB0_207:
	s_bfe_u32 s24, s11, 0x10002
	v_mov_b32_e32 v18, v199
	s_lshl_b32 s54, s24, 13
	v_ashrrev_i32_e32 v8, 3, v18
	v_add_u32_e32 v0, s54, v8
	v_mov_b64_e32 v[10:11], s[86:87]
	s_and_b32 s22, s11, 3
	s_waitcnt lgkmcnt(0)
	v_mad_i64_i32 v[0:1], s[12:13], v0, s25, v[10:11]
	s_mul_i32 s14, s24, 14
	s_lshl_b32 s12, s22, 7
	s_mov_b32 s13, s55
	v_lshlrev_b32_e32 v4, 4, v18
	s_add_i32 s15, s22, s14
	v_lshl_add_u64 v[0:1], v[0:1], 0, s[12:13]
	v_and_b32_e32 v128, 0x70, v4
	s_lshl_b32 s12, s15, 6
	v_lshl_add_u64 v[14:15], v[0:1], 0, v[128:129]
	v_ashrrev_i32_e32 v9, 31, v8
	s_addk_i32 s12, 0x280
	v_add_co_u32_e32 v0, vcc, s48, v14
	v_lshl_add_u64 v[2:3], s[12:13], 0, v[8:9]
	s_nop 0
	v_addc_co_u32_e32 v1, vcc, 0, v15, vcc
	s_mov_b32 s12, 0x79000
	v_add_co_u32_e32 v14, vcc, s12, v14
	s_and_b32 s12, s10, 3
	s_add_i32 s14, s14, s12
	s_lshl_b32 s13, s14, 6
	s_add_i32 s14, s13, 0x280
	s_lshl_b32 s26, s12, 7
	v_readfirstlane_b32 s12, v18
	s_lshl_b32 s13, s11, 4
	s_and_b32 s13, s13, 0xffffff80
	s_and_b32 s23, s12, 64
	v_and_b32_e32 v19, 31, v18
	s_or_b32 s13, s13, s23
	v_lshlrev_b64 v[2:3], 14, v[2:3]
	v_or_b32_e32 v182, s13, v19
	v_lshl_add_u64 v[2:3], s[84:85], 0, v[2:3]
	v_addc_co_u32_e32 v15, vcc, 0, v15, vcc
	s_ashr_i32 s12, s12, 1
	v_ashrrev_i32_e32 v183, 31, v182
	v_lshl_add_u64 v[12:13], v[2:3], 0, v[128:129]
	global_load_dwordx4 v[0:3], v[0:1], off offset:2560
	s_nop 0
	global_load_dwordx4 v[4:7], v[12:13], off
	global_load_dwordx4 v[130:133], v[14:15], off offset:2560
	global_load_dwordx4 v[134:137], v[12:13], off offset:128
	s_lshl_b32 s13, s22, 8
	s_andn2_b32 s12, s12, 63
	v_lshl_add_u64 v[184:185], v[182:183], 0, s[54:55]
	s_add_i32 s12, s12, s13
	v_mad_u64_u32 v[10:11], s[22:23], v184, s25, v[10:11]
	v_bfe_u32 v196, v18, 5, 1
	v_mad_i32_i24 v11, v185, s25, v11
	s_ashr_i32 s13, s12, 31
	v_lshl_add_u64 v[10:11], s[12:13], 1, v[10:11]
	v_lshlrev_b32_e32 v12, 4, v196
	v_mov_b32_e32 v13, v129
	v_lshl_add_u64 v[10:11], v[10:11], 0, v[12:13]
	s_mov_b64 s[22:23], 0x1200
	v_add_co_u32_e32 v16, vcc, s48, v10
	v_lshl_add_u64 v[14:15], v[10:11], 0, s[22:23]
	s_nop 0
	v_addc_co_u32_e32 v17, vcc, 0, v11, vcc
	s_mov_b32 s23, 0x3d000
	v_add_co_u32_e32 v10, vcc, s23, v10
	global_load_dwordx4 v[138:141], v[14:15], off offset:32
	global_load_dwordx4 v[142:145], v[14:15], off offset:64
	global_load_dwordx4 v[146:149], v[16:17], off offset:512
	global_load_dwordx4 v[150:153], v[14:15], off offset:96
	v_addc_co_u32_e32 v11, vcc, 0, v11, vcc
	global_load_dwordx4 v[154:157], v[10:11], off offset:512
	global_load_dwordx4 v[158:161], v[10:11], off offset:544
	global_load_dwordx4 v[162:165], v[10:11], off offset:576
	global_load_dwordx4 v[166:169], v[10:11], off offset:608
	v_mul_lo_u32 v10, v8, s16
	v_lshlrev_b32_e32 v11, 1, v18
	v_lshrrev_b32_e32 v13, 1, v18
	v_add3_u32 v197, v10, v128, 0
	v_and_b32_e32 v11, 8, v11
	v_and_b32_e32 v13, 4, v13
	s_mov_b32 s15, s55
	v_mov_b32_e32 v32, 0
	s_mov_b32 s22, 0
	v_mov_b32_e32 v33, v32
	v_mov_b32_e32 v34, v32
	v_mov_b32_e32 v35, v32
	v_mov_b32_e32 v36, v32
	v_mov_b32_e32 v37, v32
	v_mov_b32_e32 v38, v32
	s_waitcnt vmcnt(11)
	ds_write_b128 v197, v[0:3]
	s_waitcnt vmcnt(10)
	ds_write_b128 v197, v[4:7] offset:36864
	s_waitcnt vmcnt(9)
	ds_write_b128 v197, v[130:133] offset:9216
	s_waitcnt vmcnt(8)
	ds_write_b128 v197, v[134:137] offset:46080
	v_and_b32_e32 v0, 19, v18
	v_or3_b32 v0, v0, v11, v13
	v_mul_u32_u24_e32 v0, 0x90, v0
	v_add3_u32 v198, 0, v0, v12
	v_mul_u32_u24_e32 v0, 0x90, v19
	v_add3_u32 v200, 0, v0, v12
	v_lshl_add_u64 v[0:1], v[8:9], 0, s[14:15]
	v_lshlrev_b64 v[0:1], 14, v[0:1]
	v_or_b32_e32 v0, v0, v128
	v_lshl_add_u64 v[186:187], s[4:5], 0, v[0:1]
	v_mad_i64_i32 v[0:1], s[14:15], v8, s25, 0
	v_mad_u64_u32 v[0:1], s[14:15], s24, v222, v[0:1]
	v_or3_b32 v0, v0, s26, v128
	v_lshl_add_u64 v[188:189], s[6:7], 0, v[0:1]
	v_mov_b32_e32 v39, v32
	v_mov_b32_e32 v40, v32
	v_mov_b32_e32 v41, v32
	v_mov_b32_e32 v42, v32
	v_mov_b32_e32 v43, v32
	v_mov_b32_e32 v44, v32
	v_mov_b32_e32 v45, v32
	v_mov_b32_e32 v46, v32
	v_mov_b32_e32 v47, v32
	v_mov_b32_e32 v48, v32
	v_mov_b32_e32 v49, v32
	v_mov_b32_e32 v50, v32
	v_mov_b32_e32 v51, v32
	v_mov_b32_e32 v52, v32
	v_mov_b32_e32 v53, v32
	v_mov_b32_e32 v54, v32
	v_mov_b32_e32 v55, v32
	v_mov_b32_e32 v56, v32
	v_mov_b32_e32 v57, v32
	v_mov_b32_e32 v58, v32
	v_mov_b32_e32 v59, v32
	v_mov_b32_e32 v60, v32
	v_mov_b32_e32 v61, v32
	v_mov_b32_e32 v62, v32
	v_mov_b32_e32 v63, v32
	v_mov_b32_e32 v0, v32
	v_mov_b32_e32 v1, v32
	v_mov_b32_e32 v2, v32
	v_mov_b32_e32 v3, v32
	v_mov_b32_e32 v4, v32
	v_mov_b32_e32 v5, v32
	v_mov_b32_e32 v6, v32
	v_mov_b32_e32 v7, v32
	v_mov_b32_e32 v8, v32
	v_mov_b32_e32 v9, v32
	v_mov_b32_e32 v10, v32
	v_mov_b32_e32 v11, v32
	v_mov_b32_e32 v12, v32
	v_mov_b32_e32 v13, v32
	v_mov_b32_e32 v14, v32
	v_mov_b32_e32 v15, v32
	v_mov_b32_e32 v16, v32
	v_mov_b32_e32 v17, v32
	v_mov_b32_e32 v18, v32
	v_mov_b32_e32 v19, v32
	v_mov_b32_e32 v20, v32
	v_mov_b32_e32 v21, v32
	v_mov_b32_e32 v22, v32
	v_mov_b32_e32 v23, v32
	v_mov_b32_e32 v24, v32
	v_mov_b32_e32 v25, v32
	v_mov_b32_e32 v26, v32
	v_mov_b32_e32 v27, v32
	v_mov_b32_e32 v28, v32
	v_mov_b32_e32 v29, v32
	v_mov_b32_e32 v30, v32
	v_mov_b32_e32 v31, v32
	v_mov_b32_e32 v190, v32
	v_mov_b32_e32 v191, v32
	s_waitcnt vmcnt(0) lgkmcnt(0)
	s_barrier
	ds_read_b128 v[226:229], v198 offset:0
	ds_read_b128 v[230:233], v198 offset:32
	ds_read_b128 v[234:237], v198 offset:64
	ds_read_b128 v[238:241], v198 offset:96
	ds_read_b128 v[202:205], v200 offset:36928
	ds_read_b128 v[192:195], v200 offset:41536
	ds_read_b128 v[210:213], v200 offset:36960
	ds_read_b128 v[242:245], v200 offset:41568
	v_mov_b32_e32 v214, 0
	v_mov_b32_e32 v215, 0
	v_mov_b32_e32 v207, 0
	v_mov_b32_e32 v208, 0
	v_mov_b32_e32 v96, 0
	v_mov_b32_e32 v97, 0
	v_mov_b32_e32 v98, 0
	v_mov_b32_e32 v99, 0
	v_mov_b32_e32 v100, 0
	v_mov_b32_e32 v101, 0
	v_mov_b32_e32 v102, 0
	v_mov_b32_e32 v103, 0
	v_mov_b32_e32 v112, 0
	v_mov_b32_e32 v113, 0
	v_mov_b32_e32 v114, 0
	v_mov_b32_e32 v115, 0
	v_mov_b32_e32 v116, 0
	v_mov_b32_e32 v117, 0
	v_mov_b32_e32 v118, 0
	v_mov_b32_e32 v119, 0
	s_waitcnt lgkmcnt(4)
	v_mfma_f32_32x32x16_bf16 v[64:79], v[226:229], v[146:149], 0
	v_mfma_f32_32x32x16_bf16 v[80:95], v[226:229], v[154:157], 0
	v_mfma_f32_32x32x16_bf16 v[64:79], v[230:233], v[138:141], v[64:79]
	v_mfma_f32_32x32x16_bf16 v[80:95], v[230:233], v[158:161], v[80:95]
	v_mfma_f32_32x32x16_bf16 v[64:79], v[234:237], v[142:145], v[64:79]
	v_mfma_f32_32x32x16_bf16 v[80:95], v[234:237], v[162:165], v[80:95]
	v_mfma_f32_32x32x16_bf16 v[64:79], v[238:241], v[150:153], v[64:79]
	v_mfma_f32_32x32x16_bf16 v[80:95], v[238:241], v[166:169], v[80:95]
	s_nop 7
	v_readfirstlane_b32 s23, v199
	s_nop 3
	s_cmpk_lt_u32 s23, 0x100
	s_cbranch_scc1 .Lc_noprio
	s_setprio 1
.Lc_noprio:
.Lc_top:
	s_cmpk_gt_u32 s22, 0x7d
	s_cbranch_scc1 .Lc_noload
	global_load_dwordx4 v[130:133], v[188:189], off
	global_load_dwordx4 v[134:137], v[186:187], off

; __device__ __forceinline__ void attn_c_unit(LAS unsigned char* lds, const bf16_t* proj, const bf16_t* vt, bf16_t* obuf, int b, int hk, int blk, float mref, unsigned long long* sg) {
;     ...
;     for (int it = 0; it < nT; ++it) {
;         const int buf = it & 3;
;         if (it + 2 < nT) { kreg = *(const u32x4*)(kg + (size_t)((it + 2) * 64) * INW); vreg = *(const u32x4*)(vg + (it + 2) * 64); }
;         const LAS unsigned char* kb = lds + CK + buf * ATT_TILE + pr * KP + 16 * h;
;         f32x16 s00, s01, s10, s11;
;         {
;             const bf16x8 a0 = *(const LAS bf16x8*)(kb), a1 = *(const LAS bf16x8*)(kb + 32 * KP);
;             s00 = __builtin_amdgcn_mfma_f32_32x32x16_bf16(a0, qf[0][0], negm, 0, 0, 0);
;             s10 = __builtin_amdgcn_mfma_f32_32x32x16_bf16(a0, qf[1][0], negm, 0, 0, 0);
;             s01 = __builtin_amdgcn_mfma_f32_32x32x16_bf16(a1, qf[0][0], negm, 0, 0, 0);
;             s11 = __builtin_amdgcn_mfma_f32_32x32x16_bf16(a1, qf[1][0], negm, 0, 0, 0);
;         }
; #pragma unroll
;         for (int ks = 1; ks < 4; ++ks) {
;             const bf16x8 a0 = *(const LAS bf16x8*)(kb + 32 * ks), a1 = *(const LAS bf16x8*)(kb + 32 * KP + 32 * ks);
;             s00 = __builtin_amdgcn_mfma_f32_32x32x16_bf16(a0, qf[0][ks], s00, 0, 0, 0);
;             s10 = __builtin_amdgcn_mfma_f32_32x32x16_bf16(a0, qf[1][ks], s10, 0, 0, 0);
;             s01 = __builtin_amdgcn_mfma_f32_32x32x16_bf16(a1, qf[0][ks], s01, 0, 0, 0);
;             s11 = __builtin_amdgcn_mfma_f32_32x32x16_bf16(a1, qf[1][ks], s11, 0, 0, 0);
;         }
;         u32x4 pw0[4], pw1[4];
;         {
;             float ps = 0.f;
; #pragma unroll
;             for (int i = 0; i < 16; ++i) { s00[i] = __builtin_amdgcn_exp2f(s00[i]); s01[i] = __builtin_amdgcn_exp2f(s01[i]); ps += s00[i] + s01[i]; }
;             l0 += ps;
; #pragma unroll
;             for (int q = 0; q < 4; ++q) { pw0[0][q] = pk_bf16(s00[2 * q], s00[2 * q + 1]); pw0[1][q] = pk_bf16(s00[8 + 2 * q], s00[8 + 2 * q + 1]);
;                                           pw0[2][q] = pk_bf16(s01[2 * q], s01[2 * q + 1]); pw0[3][q] = pk_bf16(s01[8 + 2 * q], s01[8 + 2 * q + 1]); }
;         }
;         {
;             float ps = 0.f;
; #pragma unroll
;             for (int i = 0; i < 16; ++i) { s10[i] = __builtin_amdgcn_exp2f(s10[i]); s11[i] = __builtin_amdgcn_exp2f(s11[i]); ps += s10[i] + s11[i]; }
;             l1 += ps;
; #pragma unroll
.Lc_nobar:
	s_add_i32 s23, s22, 1
	s_and_b32 s23, s23, 3
	s_mulk_i32 s23, 0x2400
	v_add_u32_e32 v128, s23, v198
	ds_read_b128 v[226:229], v128 offset:0
	ds_read_b128 v[230:233], v128 offset:32
	ds_read_b128 v[234:237], v128 offset:64
	ds_read_b128 v[238:241], v128 offset:96
	s_waitcnt lgkmcnt(4)
	v_mfma_f32_32x32x16_bf16 v[32:47], v[202:205], v[64:67], v[32:47]
	v_exp_f32_e32 v96, v96
	v_exp_f32_e32 v97, v97
	v_exp_f32_e32 v98, v98
	v_exp_f32_e32 v99, v99
	v_add_f32_e32 v190, v190, v96
	v_mfma_f32_32x32x16_bf16 v[0:15], v[202:205], v[80:83], v[0:15]
	v_add_f32_e32 v214, v214, v97
	v_cvt_pk_bf16_f32 v96, v96, v97
	v_exp_f32_e32 v100, v100
	v_exp_f32_e32 v101, v101
	v_add_f32_e32 v190, v190, v98
	v_mfma_f32_32x32x16_bf16 v[48:63], v[192:195], v[64:67], v[48:63]
	v_add_f32_e32 v214, v214, v99
	v_cvt_pk_bf16_f32 v97, v98, v99
	v_exp_f32_e32 v102, v102
	v_exp_f32_e32 v103, v103
	v_add_f32_e32 v190, v190, v100
	v_mfma_f32_32x32x16_bf16 v[16:31], v[192:195], v[80:83], v[16:31]
	v_add_f32_e32 v214, v214, v101
	v_cvt_pk_bf16_f32 v98, v100, v101
	v_exp_f32_e32 v104, v104
	v_exp_f32_e32 v105, v105
	v_add_f32_e32 v190, v190, v102
	v_mfma_f32_32x32x16_bf16 v[32:47], v[210:213], v[68:71], v[32:47]
	v_add_f32_e32 v214, v214, v103
	v_cvt_pk_bf16_f32 v99, v102, v103
	v_exp_f32_e32 v106, v106
	v_exp_f32_e32 v107, v107
	v_add_f32_e32 v190, v190, v104
	v_mfma_f32_32x32x16_bf16 v[0:15], v[210:213], v[84:87], v[0:15]
	v_add_f32_e32 v214, v214, v105
	v_cvt_pk_bf16_f32 v100, v104, v105
	v_exp_f32_e32 v108, v108
	v_exp_f32_e32 v109, v109
	v_add_f32_e32 v190, v190, v106
	v_mfma_f32_32x32x16_bf16 v[48:63], v[242:245], v[68:71], v[48:63]
	v_add_f32_e32 v214, v214, v107
	v_cvt_pk_bf16_f32 v101, v106, v107
	v_exp_f32_e32 v110, v110
	v_exp_f32_e32 v111, v111
	v_add_f32_e32 v190, v190, v108
	v_mfma_f32_32x32x16_bf16 v[16:31], v[242:245], v[84:87], v[16:31]
	ds_read_b128 v[202:205], v246 offset:36928
	ds_read_b128 v[192:195], v246 offset:41536
	ds_read_b128 v[210:213], v246 offset:36960
	ds_read_b128 v[242:245], v246 offset:41568
	s_waitcnt lgkmcnt(4)
	v_add_f32_e32 v214, v214, v109
	v_cvt_pk_bf16_f32 v102, v108, v109
	v_add_f32_e32 v190, v190, v110
	v_add_f32_e32 v214, v214, v111
	v_cvt_pk_bf16_f32 v103, v110, v111
	v_mfma_f32_32x32x16_bf16 v[64:79], v[226:229], v[146:149], 0
	v_exp_f32_e32 v112, v112
	v_exp_f32_e32 v113, v113
	v_exp_f32_e32 v114, v114
	v_exp_f32_e32 v115, v115
	v_add_f32_e32 v191, v191, v112
	v_mfma_f32_32x32x16_bf16 v[80:95], v[226:229], v[154:157], 0
	v_add_f32_e32 v215, v215, v113
	v_cvt_pk_bf16_f32 v112, v112, v113
	v_exp_f32_e32 v116, v116
	v_exp_f32_e32 v117, v117
	v_add_f32_e32 v191, v191, v114
	v_mfma_f32_32x32x16_bf16 v[64:79], v[230:233], v[138:141], v[64:79]
	v_add_f32_e32 v215, v215, v115
	v_cvt_pk_bf16_f32 v113, v114, v115
	v_exp_f32_e32 v118, v118
	v_exp_f32_e32 v119, v119
	v_add_f32_e32 v191, v191, v116
	v_mfma_f32_32x32x16_bf16 v[80:95], v[230:233], v[158:161], v[80:95]
	v_add_f32_e32 v215, v215, v117
	v_cvt_pk_bf16_f32 v114, v116, v117
	v_exp_f32_e32 v120, v120
	v_exp_f32_e32 v121, v121
	v_add_f32_e32 v191, v191, v118
	v_mfma_f32_32x32x16_bf16 v[64:79], v[234:237], v[142:145], v[64:79]
	v_add_f32_e32 v215, v215, v119
	v_cvt_pk_bf16_f32 v115, v118, v119
	v_exp_f32_e32 v122, v122
	v_exp_f32_e32 v123, v123
	v_add_f32_e32 v191, v191, v120
	v_mfma_f32_32x32x16_bf16 v[80:95], v[234:237], v[162:165], v[80:95]
	v_add_f32_e32 v215, v215, v121
	v_cvt_pk_bf16_f32 v116, v120, v121
	v_exp_f32_e32 v124, v124
	v_exp_f32_e32 v125, v125
	v_add_f32_e32 v191, v191, v122
	v_mfma_f32_32x32x16_bf16 v[64:79], v[238:241], v[150:153], v[64:79]
	v_add_f32_e32 v215, v215, v123
	v_cvt_pk_bf16_f32 v117, v122, v123
	v_exp_f32_e32 v126, v126
	v_exp_f32_e32 v127, v127
	v_add_f32_e32 v191, v191, v124
	v_mfma_f32_32x32x16_bf16 v[80:95], v[238:241], v[166:169], v[80:95]
	v_add_f32_e32 v215, v215, v125
	v_cvt_pk_bf16_f32 v118, v124, v125
	v_add_f32_e32 v191, v191, v126
	v_add_f32_e32 v215, v215, v127
	v_cvt_pk_bf16_f32 v119, v126, v127
	s_add_i32 s22, s22, 1
	v_lshl_add_u64 v[186:187], v[186:187], 0, s[64:65]
	v_lshl_add_u64 v[188:189], v[188:189], 0, s[68:69]
	s_cmpk_eq_i32 s22, 0x80
	s_cbranch_scc0 .Lc_top
	s_waitcnt lgkmcnt(0)
	v_mfma_f32_32x32x16_bf16 v[32:47], v[202:205], v[96:99], v[32:47]
	v_mfma_f32_32x32x16_bf16 v[0:15], v[202:205], v[112:115], v[0:15]
	v_mfma_f32_32x32x16_bf16 v[48:63], v[192:195], v[96:99], v[48:63]
	v_mfma_f32_32x32x16_bf16 v[16:31], v[192:195], v[112:115], v[16:31]
	v_mfma_f32_32x32x16_bf16 v[32:47], v[210:213], v[100:103], v[32:47]
	v_mfma_f32_32x32x16_bf16 v[0:15], v[210:213], v[116:119], v[0:15]
	v_mfma_f32_32x32x16_bf16 v[48:63], v[242:245], v[100:103], v[48:63]
	v_mfma_f32_32x32x16_bf16 v[16:31], v[242:245], v[116:119], v[16:31]
	v_add_f32_e32 v190, v190, v214
	v_add_f32_e32 v191, v191, v215
	s_setprio 0
	s_barrier
